# cache_k/cache_v f32->bf16 conversion jobs (2048 jobs, used from phase 3) moved out of phase 0 onto the phase-1 idle blocks, hand-written pipelined loop
# speedup vs baseline: 1.0312x; 1.0174x over previous
.LBB0_24:
	s_cmpk_lt_i32 s28, 0x35a0
	s_mov_b64 s[8:9], -1
	s_cbranch_scc0 .LBB0_73
	s_cmpk_gt_i32 s28, 0x97f
	s_cbranch_scc0 .LBB0_62
	s_cmpk_gt_u32 s28, 0x347f
	s_cbranch_scc0 .LBB0_23
	s_cmpk_gt_u32 s28, 0x307f
	s_cbranch_scc0 .LBB0_41
	s_cmpk_gt_u32 s28, 0x347f
	s_cbranch_scc0 .LBB0_38
	s_cmpk_gt_u32 s28, 0x34ff
	s_cbranch_scc0 .LBB0_35
	s_cmpk_gt_u32 s28, 0x357f
	s_cbranch_scc0 .LBB0_32
	s_load_dwordx16 s[36:51], s[0:1], 0xc0
	v_add_u32_e32 v65, s60, v69
	v_add_u32_e32 v66, 0xf9500000, v65
	v_mov_b32_e32 v67, v17
	v_add_u32_e32 v104, 0xf9500800, v65
	s_waitcnt lgkmcnt(0)
	v_lshl_add_u64 v[4:5], v[66:67], 2, s[46:47]
	v_mov_b32_e32 v105, v17
	v_add_u32_e32 v106, 0xf9501000, v65
	v_mov_b32_e32 v107, v17
	v_add_u32_e32 v108, 0xf9501800, v65
	v_mov_b32_e32 v109, v17
	global_load_dwordx4 v[0:3], v[4:5], off offset:16
	s_nop 0
	global_load_dwordx4 v[4:7], v[4:5], off
	v_lshl_add_u64 v[12:13], v[104:105], 2, s[46:47]
	v_lshl_add_u64 v[92:93], v[106:107], 2, s[46:47]
	v_lshl_add_u64 v[100:101], v[108:109], 2, s[46:47]
	global_load_dwordx4 v[8:11], v[12:13], off offset:16
	s_nop 0
	global_load_dwordx4 v[12:15], v[12:13], off
	s_nop 0
	global_load_dwordx4 v[88:91], v[92:93], off offset:16
	s_nop 0
	global_load_dwordx4 v[92:95], v[92:93], off
	s_nop 0
	global_load_dwordx4 v[96:99], v[100:101], off
	s_nop 0
	global_load_dwordx4 v[100:103], v[100:101], off offset:16
	v_lshl_add_u64 v[66:67], v[66:67], 1, s[14:15]
	v_lshl_add_u64 v[104:105], v[104:105], 1, s[14:15]
	v_lshl_add_u64 v[106:107], v[106:107], 1, s[14:15]
	v_lshl_add_u64 v[108:109], v[108:109], 1, s[14:15]
	s_mov_b64 s[8:9], 0
	s_waitcnt vmcnt(6)
	v_cvt_pk_bf16_f32 v4, v4, v5
	v_cvt_pk_bf16_f32 v5, v6, v7
	v_cvt_pk_bf16_f32 v6, v0, v1
	v_cvt_pk_bf16_f32 v7, v2, v3
	s_waitcnt vmcnt(4)
	v_cvt_pk_bf16_f32 v0, v12, v13
	v_cvt_pk_bf16_f32 v1, v14, v15
	v_cvt_pk_bf16_f32 v2, v8, v9
	v_cvt_pk_bf16_f32 v3, v10, v11
	s_waitcnt vmcnt(2)
	v_cvt_pk_bf16_f32 v8, v92, v93
	v_cvt_pk_bf16_f32 v9, v94, v95
	v_cvt_pk_bf16_f32 v10, v88, v89
	v_cvt_pk_bf16_f32 v11, v90, v91
	s_waitcnt vmcnt(1)
	v_cvt_pk_bf16_f32 v12, v96, v97
	v_cvt_pk_bf16_f32 v13, v98, v99
	s_waitcnt vmcnt(0)
	v_cvt_pk_bf16_f32 v14, v100, v101
	v_cvt_pk_bf16_f32 v15, v102, v103
	global_store_dwordx4 v[66:67], v[4:7], off
	global_store_dwordx4 v[104:105], v[0:3], off
	global_store_dwordx4 v[106:107], v[8:11], off
	global_store_dwordx4 v[108:109], v[12:15], off

.Lta_done:
	s_cmp_lt_u32 s2, 0x128
	s_cbranch_scc1 .Lcvt_done
	s_cmp_ge_u32 s2, 0x1e0
	s_cbranch_scc1 .Lcvt_done
	s_load_dwordx2 s[30:31], s[0:1], 0x18
	s_load_dwordx2 s[32:33], s[0:1], 0x20
	v_lshlrev_b32_e32 v0, 5, v204
	v_lshlrev_b32_e32 v1, 4, v204
	v_add_u32_e32 v2, 0x0, v0
	v_add_u32_e32 v6, 0x0, v1
	v_add_u32_e32 v3, 0x2000, v0
	v_add_u32_e32 v7, 0x1000, v1
	v_add_u32_e32 v4, 0x4000, v0
	v_add_u32_e32 v8, 0x2000, v1
	v_add_u32_e32 v5, 0x6000, v0
	v_add_u32_e32 v9, 0x3000, v1
	s_sub_u32 s4, s2, 0x128
	s_waitcnt lgkmcnt(0)
	s_cmpk_lt_u32 s4, 0x400
	s_cselect_b32 s18, s30, s32
	s_cselect_b32 s19, s31, s33
	s_mov_b32 s9, 0x1b008000
	s_cselect_b32 s20, 0x19f08000, s9
	s_and_b32 s5, s4, 0x3ff
	s_lshr_b32 s6, s5, 7
	s_and_b32 s7, s5, 127
	s_lshl_b32 s8, s6, 22
	s_lshl_b32 s9, s7, 15
	s_add_u32 s8, s8, s9
	s_add_u32 s10, s18, s8
	s_addc_u32 s11, s19, 0
	s_mul_i32 s8, s6, 0x220000
	s_lshl_b32 s9, s7, 14
	s_add_u32 s8, s8, s9
	s_add_u32 s8, s8, s20
	s_add_u32 s14, s94, s8
	s_addc_u32 s15, s95, 0
	global_load_dwordx4 v[16:19], v2, s[10:11]
	global_load_dwordx4 v[20:23], v2, s[10:11] offset:16
	global_load_dwordx4 v[24:27], v3, s[10:11]
	global_load_dwordx4 v[28:31], v3, s[10:11] offset:16
	global_load_dwordx4 v[32:35], v4, s[10:11]
	global_load_dwordx4 v[36:39], v4, s[10:11] offset:16
	global_load_dwordx4 v[40:43], v5, s[10:11]
	global_load_dwordx4 v[44:47], v5, s[10:11] offset:16
.Lcvt_loop:
	s_add_u32 s12, s4, 184
	s_cmpk_lt_u32 s12, 0x800
	s_cselect_b32 s13, s12, s4
	s_cmpk_lt_u32 s13, 0x400
	s_cselect_b32 s18, s30, s32
	s_cselect_b32 s19, s31, s33
	s_mov_b32 s9, 0x1b008000
	s_cselect_b32 s20, 0x19f08000, s9
	s_and_b32 s5, s13, 0x3ff
	s_lshr_b32 s6, s5, 7
	s_and_b32 s7, s5, 127
	s_lshl_b32 s8, s6, 22
	s_lshl_b32 s9, s7, 15
	s_add_u32 s8, s8, s9
	s_add_u32 s10, s18, s8
	s_addc_u32 s11, s19, 0
	s_mul_i32 s8, s6, 0x220000
	s_lshl_b32 s9, s7, 14
	s_add_u32 s8, s8, s9
	s_add_u32 s8, s8, s20
	s_add_u32 s16, s94, s8
	s_addc_u32 s17, s95, 0
	global_load_dwordx4 v[48:51], v2, s[10:11]
	global_load_dwordx4 v[52:55], v2, s[10:11] offset:16
	global_load_dwordx4 v[56:59], v3, s[10:11]
	global_load_dwordx4 v[60:63], v3, s[10:11] offset:16
	global_load_dwordx4 v[64:67], v4, s[10:11]
	global_load_dwordx4 v[68:71], v4, s[10:11] offset:16
	global_load_dwordx4 v[72:75], v5, s[10:11]
	global_load_dwordx4 v[76:79], v5, s[10:11] offset:16
	s_waitcnt vmcnt(8)
	v_cvt_pk_bf16_f32 v80, v16, v17
	v_cvt_pk_bf16_f32 v81, v18, v19
	v_cvt_pk_bf16_f32 v82, v20, v21
	v_cvt_pk_bf16_f32 v83, v22, v23
	v_cvt_pk_bf16_f32 v84, v24, v25
	v_cvt_pk_bf16_f32 v85, v26, v27
	v_cvt_pk_bf16_f32 v86, v28, v29
	v_cvt_pk_bf16_f32 v87, v30, v31
	v_cvt_pk_bf16_f32 v88, v32, v33
	v_cvt_pk_bf16_f32 v89, v34, v35
	v_cvt_pk_bf16_f32 v90, v36, v37
	v_cvt_pk_bf16_f32 v91, v38, v39
	v_cvt_pk_bf16_f32 v92, v40, v41
	v_cvt_pk_bf16_f32 v93, v42, v43
	v_cvt_pk_bf16_f32 v94, v44, v45
	v_cvt_pk_bf16_f32 v95, v46, v47
	global_store_dwordx4 v6, v[80:83], s[14:15]
	global_store_dwordx4 v7, v[84:87], s[14:15]
	global_store_dwordx4 v8, v[88:91], s[14:15]
	global_store_dwordx4 v9, v[92:95], s[14:15]
	s_mov_b32 s4, s12
	s_cmpk_lt_u32 s4, 0x800
	s_cbranch_scc0 .Lcvt_drain
	s_add_u32 s12, s4, 184
	s_cmpk_lt_u32 s12, 0x800
	s_cselect_b32 s13, s12, s4
	s_cmpk_lt_u32 s13, 0x400
	s_cselect_b32 s18, s30, s32
	s_cselect_b32 s19, s31, s33
	s_mov_b32 s9, 0x1b008000
	s_cselect_b32 s20, 0x19f08000, s9
	s_and_b32 s5, s13, 0x3ff
	s_lshr_b32 s6, s5, 7
	s_and_b32 s7, s5, 127
	s_lshl_b32 s8, s6, 22
	s_lshl_b32 s9, s7, 15
	s_add_u32 s8, s8, s9
	s_add_u32 s10, s18, s8
	s_addc_u32 s11, s19, 0
	s_mul_i32 s8, s6, 0x220000
	s_lshl_b32 s9, s7, 14
	s_add_u32 s8, s8, s9
	s_add_u32 s8, s8, s20
	s_add_u32 s14, s94, s8
	s_addc_u32 s15, s95, 0
	global_load_dwordx4 v[16:19], v2, s[10:11]
	global_load_dwordx4 v[20:23], v2, s[10:11] offset:16
	global_load_dwordx4 v[24:27], v3, s[10:11]
	global_load_dwordx4 v[28:31], v3, s[10:11] offset:16
	global_load_dwordx4 v[32:35], v4, s[10:11]
	global_load_dwordx4 v[36:39], v4, s[10:11] offset:16
	global_load_dwordx4 v[40:43], v5, s[10:11]
	global_load_dwordx4 v[44:47], v5, s[10:11] offset:16
	s_waitcnt vmcnt(8)
	v_cvt_pk_bf16_f32 v80, v48, v49
	v_cvt_pk_bf16_f32 v81, v50, v51
	v_cvt_pk_bf16_f32 v82, v52, v53
	v_cvt_pk_bf16_f32 v83, v54, v55
	v_cvt_pk_bf16_f32 v84, v56, v57
	v_cvt_pk_bf16_f32 v85, v58, v59
	v_cvt_pk_bf16_f32 v86, v60, v61
	v_cvt_pk_bf16_f32 v87, v62, v63
	v_cvt_pk_bf16_f32 v88, v64, v65
	v_cvt_pk_bf16_f32 v89, v66, v67
	v_cvt_pk_bf16_f32 v90, v68, v69
	v_cvt_pk_bf16_f32 v91, v70, v71
	v_cvt_pk_bf16_f32 v92, v72, v73
	v_cvt_pk_bf16_f32 v93, v74, v75
	v_cvt_pk_bf16_f32 v94, v76, v77
	v_cvt_pk_bf16_f32 v95, v78, v79
	global_store_dwordx4 v6, v[80:83], s[16:17]
	global_store_dwordx4 v7, v[84:87], s[16:17]
	global_store_dwordx4 v8, v[88:91], s[16:17]
	global_store_dwordx4 v9, v[92:95], s[16:17]
	s_mov_b32 s4, s12
	s_cmpk_lt_u32 s4, 0x800
	s_cbranch_scc0 .Lcvt_drain
	s_branch .Lcvt_loop
.Lcvt_drain:
	s_waitcnt vmcnt(0)
.Lcvt_done:
	s_load_dword s3, s[0:1], 0x120
	s_add_u32 s4, s0, 0x120
	s_addc_u32 s5, s1, 0
	s_waitcnt lgkmcnt(0)
	s_load_dwordx4 s[28:31], s[0:1], 0x110
	v_readlane_b32 s8, v244, 1
	v_readlane_b32 s9, v244, 2
	s_waitcnt lgkmcnt(0)
	s_cmp_lt_i32 s29, 3
	s_cselect_b64 s[6:7], -1, 0
	s_xor_b64 s[8:9], s[8:9], -1
	s_or_b64 s[6:7], s[6:7], s[8:9]
	s_and_b64 vcc, exec, s[6:7]
	s_cbranch_vccnz .LBB0_181
	s_waitcnt vmcnt(0)
	s_waitcnt vmcnt(63) expcnt(7) lgkmcnt(15)
	s_barrier
	s_and_saveexec_b64 s[6:7], s[56:57]
	s_cbranch_execz .LBB0_180
	v_readlane_b32 s8, v244, 0
	s_waitcnt vmcnt(0) expcnt(0) lgkmcnt(0)
	s_nop 0
	v_mov_b32_e32 v0, s8
	ds_read_b32 v2, v0
	ds_read_b32 v0, v0 offset:4
	s_waitcnt lgkmcnt(1)
	v_cmp_ne_u32_e32 vcc, 0, v2
	s_cbranch_vccnz .LBB0_151
	s_load_dwordx2 s[10:11], s[4:5], 0x4
	s_add_u32 s4, s58, 0x1000
	s_addc_u32 s5, s59, 0
	s_add_u32 s8, s58, 0x1100
	s_addc_u32 s9, s59, 0
	s_waitcnt lgkmcnt(0)
	s_mul_i32 s3, s10, s3
	s_add_u32 s10, s58, 0x1200
	s_mul_i32 s3, s3, s11
	s_addc_u32 s11, s59, 0
	s_add_u32 s12, s58, 0x1300
	s_addc_u32 s13, s59, 0
	s_mov_b32 s16, 1
	v_mov_b32_e32 v16, 0
	s_branch .LBB0_141
